# last grid barrier without L2 write-back/invalidate when the XCD holds its blockIdx%8 group (runtime XCC check); final phase takes its own XCD's rows
# baseline (speedup 1.0000x reference)
; #define LAS __attribute__((address_space(3)))
; __device__ __forceinline__ unsigned xb_add(unsigned* p, unsigned v) { return __hip_atomic_fetch_add(p, v, __ATOMIC_RELAXED, __HIP_MEMORY_SCOPE_AGENT); }
; __device__ __forceinline__ unsigned xb_xcc_id() { return (unsigned)__builtin_amdgcn_s_getreg((3 << 11) | 20) & 0xFu; }
; __device__ __forceinline__ XcdBarrier xcd_barrier_post(unsigned* bar, volatile LAS unsigned* st) {
;     XcdBarrier b; b.bar = bar; b.x = xb_xcc_id(); b.st = st;
;     if (threadIdx.x == 0) (void)xb_add(&bar[XB_XCNT(b.x)], 1u);
;     return b;
; __global__ void __launch_bounds__(NTHR, 2) hymba_fwd(Params p) {
;     ...
;     volatile LAS unsigned* bst = (volatile LAS unsigned*)(lds + 131072);
;     if (threadIdx.x < 4) bst[threadIdx.x] = 0u;
;     __syncthreads();
;     const XcdBarrier bar = xcd_barrier_post((unsigned*)(p.ws + WS_BAR), bst);
_Z9hymba_fwd6Params:
	s_load_dwordx4 s[68:71], s[0:1], 0x80
	s_load_dwordx2 s[72:73], s[0:1], 0x90
	v_cmp_gt_u32_e32 vcc, 4, v0
	s_and_saveexec_b64 s[4:5], vcc
	v_lshl_add_u32 v1, v0, 2, 0
	v_add_u32_e32 v1, 0x20000, v1
	v_mov_b32_e32 v2, 0
	ds_write_b32 v1, v2
	s_or_b64 exec, exec, s[4:5]
	s_waitcnt lgkmcnt(0)
	s_barrier
	s_add_u32 s74, s70, 0xc80000
	s_getreg_b32 s3, hwreg(HW_REG_XCC_ID, 0, 4)
	s_addc_u32 s75, s71, 0
	s_and_b32 s33, s3, 15
	v_cmp_eq_u32_e64 s[86:87], 0, v0
	s_and_saveexec_b64 s[6:7], s[86:87]
	s_cbranch_execz .LBB0_5
	s_mov_b64 s[8:9], exec
	v_mbcnt_lo_u32_b32 v1, s8, 0
	v_mbcnt_hi_u32_b32 v1, s9, v1
	v_cmp_eq_u32_e32 vcc, 0, v1
	s_and_b64 s[10:11], exec, vcc
	s_mov_b64 exec, s[10:11]
	s_cbranch_execz .LBB0_5
	s_lshl_b32 s3, s33, 8
	s_bcnt1_i32_b64 s8, s[8:9]
	v_mov_b32_e32 v1, s3
	v_mov_b32_e32 v2, s8
	global_atomic_add v1, v2, s[74:75] offset:1024
	s_and_b32 s3, s2, 7
	s_lshl_b32 s3, s3, 7
	s_add_i32 s3, s3, 0x44
	s_lshl_b32 s8, 1, s33
	v_mov_b32_e32 v3, s3
	v_mov_b32_e32 v4, s8
	global_atomic_or v3, v4, s[74:75]

; __device__ __forceinline__ unsigned xb_ld(unsigned* p)              { return __hip_atomic_load(p, __ATOMIC_RELAXED, __HIP_MEMORY_SCOPE_AGENT); }
; __device__ __forceinline__ void xcd_barrier_complete(unsigned* bar, unsigned x, unsigned& nloc, unsigned& nx) {
;     const unsigned G = gridDim.x * gridDim.y * gridDim.z;
;     unsigned sum, cnt, mine, sp = 0u;
;     for (;;) {
;         sum = 0u; cnt = 0u; mine = 0u;
; #pragma unroll
;         for (unsigned j = 0; j < 16; ++j) { const unsigned c = xb_ld(&bar[XB_XCNT(j)]); sum += c; cnt += (c > 0u) ? 1u : 0u; mine = (j == x) ? c : mine; }
;         if (sum == G) break;
;         __builtin_amdgcn_s_sleep(1);
;         if ((++sp & 255u) == 0u) { if (xb_ld(&bar[XB_TMO])) break; if (sp > XB_SPIN_CAP) { atomicAdd(&bar[XB_TMO], 1u); break; } }
;     }
;     nloc = mine > 0u ? mine : 1u; nx = cnt > 0u ? cnt : 1u;
; __device__ __forceinline__ void xcd_barrier(const XcdBarrier& b) {
;     ...
;     if (threadIdx.x == 0) {
;         unsigned* bar = b.bar;
;         __builtin_amdgcn_s_waitcnt(0);
;         unsigned nloc = b.st[0], nx = b.st[1];
;         if (nloc == 0u) { xcd_barrier_complete(bar, b.x, nloc, nx); b.st[0] = nloc; b.st[1] = nx; }
.LBB0_455:
	s_load_dword s100, s[0:1], 0x98
	s_and_b32 s4, s2, 7
	s_lshl_b32 s4, s4, 7
	s_add_i32 s4, s4, 0x44
	v_mov_b32_e32 v224, s4
	global_load_dword v225, v224, s[74:75] sc1
	s_waitcnt vmcnt(0) lgkmcnt(0)
	v_readfirstlane_b32 s4, v225
	s_bcnt1_i32_b32 s4, s4
	s_cmp_eq_u32 s4, 1
	s_cselect_b32 s4, 2, 0
	s_cmp_eq_u32 s100, 0x100
	s_cselect_b32 s100, 1, 0
	s_cselect_b32 s4, s4, 0
	s_or_b32 s100, s100, s4
	s_cmp_gt_i32 s73, 6
	s_cselect_b64 s[6:7], -1, 0
	s_and_b64 s[8:9], s[10:11], s[6:7]
	s_andn2_b64 vcc, exec, s[8:9]
	s_cbranch_vccnz .LBB0_509
	s_waitcnt vmcnt(0)
	s_waitcnt vmcnt(0) lgkmcnt(0)
	s_barrier
	s_and_saveexec_b64 s[8:9], s[86:87]
	s_cbranch_execz .LBB0_508
	s_add_i32 s3, 0, 0x20000
	v_mov_b32_e32 v1, s3
	s_waitcnt vmcnt(0) expcnt(0) lgkmcnt(0)
	ds_read_b32 v3, v1
	s_add_i32 s3, 0, 0x20004
	v_mov_b32_e32 v1, s3
	ds_read_b32 v1, v1
	s_waitcnt lgkmcnt(1)
	v_cmp_ne_u32_e32 vcc, 0, v3
	s_cbranch_vccnz .LBB0_472
	s_load_dwordx2 s[12:13], s[0:1], 0x98
	s_load_dword s3, s[0:1], 0xa0
	s_add_u32 s4, s70, 0xc80200
	s_addc_u32 s5, s71, 0
	s_add_u32 s10, s70, 0xc80400
	s_waitcnt lgkmcnt(0)
	s_mul_i32 s11, s13, s12
	s_mul_i32 s3, s11, s3
	s_addc_u32 s11, s71, 0
	s_add_u32 s12, s70, 0xc80500
	s_addc_u32 s13, s71, 0
	s_add_u32 s14, s70, 0xc80600
	s_addc_u32 s15, s71, 0
	s_add_u32 s16, s70, 0xc80700
	s_addc_u32 s17, s71, 0
	s_add_u32 s18, s70, 0xc80800
	s_addc_u32 s19, s71, 0
	s_add_u32 s20, s70, 0xc80900
	s_addc_u32 s21, s71, 0
	s_add_u32 s22, s70, 0xc80a00
	s_addc_u32 s23, s71, 0
	s_add_u32 s24, s70, 0xc80b00
	s_addc_u32 s25, s71, 0
	s_add_u32 s26, s70, 0xc80c00
	s_addc_u32 s27, s71, 0
	s_add_u32 s28, s70, 0xc80d00
	s_addc_u32 s29, s71, 0
	s_add_u32 s30, s70, 0xc80e00
	s_addc_u32 s31, s71, 0
	s_add_u32 s34, s70, 0xc80f00
	s_addc_u32 s35, s71, 0
	s_add_u32 s38, s70, 0xc81000
	s_addc_u32 s39, s71, 0
	s_add_u32 s40, s70, 0xc81100
	s_addc_u32 s41, s71, 0
	s_add_u32 s42, s70, 0xc81200
	s_addc_u32 s43, s71, 0
	s_add_u32 s44, s70, 0xc81300
	s_addc_u32 s45, s71, 0
	s_mov_b32 s54, 1
	v_mov_b32_e32 v17, 0
	s_branch .LBB0_460

; __device__ __forceinline__ unsigned xb_ld(unsigned* p)              { return __hip_atomic_load(p, __ATOMIC_RELAXED, __HIP_MEMORY_SCOPE_AGENT); }
; #define XB_SPIN(cond, bar) do { unsigned _sp = 0; while (cond) { __builtin_amdgcn_s_sleep(1); \
;     if ((++_sp & 255u) == 0u) { if (xb_ld(&(bar)[XB_TMO])) break; if (_sp > XB_SPIN_CAP) { atomicAdd(&(bar)[XB_TMO], 1u); break; } } } } while (0)
; __device__ __forceinline__ void xcd_barrier(const XcdBarrier& b) {
;     ...
;             XB_SPIN(xb_ld(&bar[XB_XGEN(b.x)]) == gen, bar);
;             __builtin_amdgcn_fence(__ATOMIC_ACQUIRE, "agent");
;             asm volatile("s_waitcnt vmcnt(0)" ::: "memory");
.LBB0_487:
	s_or_b64 exec, exec, s[12:13]
	s_waitcnt vmcnt(0)
	s_bitcmp1_b32 s100, 1
	s_cbranch_scc1 .Llb_2
	buffer_inv sc1

; __device__ __forceinline__ unsigned xb_add(unsigned* p, unsigned v) { return __hip_atomic_fetch_add(p, v, __ATOMIC_RELAXED, __HIP_MEMORY_SCOPE_AGENT); }
; __device__ __forceinline__ void xcd_barrier(const XcdBarrier& b) {
;     ...
;         if (old + 1u == (gen + 1u) * nloc) {
;             __builtin_amdgcn_fence(__ATOMIC_RELEASE, "agent");
;             asm volatile("s_waitcnt vmcnt(0)" ::: "memory");
;             const unsigned og = xb_add(&bar[XB_TOP], 1u);
;             const unsigned tg = og / nx;
;             if (og + 1u == (tg + 1u) * nx) xb_add(&bar[XB_TOPGEN], 1u);
.LBB0_488:
	s_andn2_saveexec_b64 s[10:11], s[10:11]
	s_cbranch_execz .LBB0_508
	s_mov_b64 s[10:11], exec
	s_bitcmp1_b32 s100, 1
	s_cbranch_scc1 .Llb_1
	buffer_wbl2 sc1
.Llb_1:
	s_waitcnt lgkmcnt(0)
	s_waitcnt vmcnt(0)
	v_mbcnt_lo_u32_b32 v2, s10, 0
	v_mbcnt_hi_u32_b32 v2, s11, v2
	v_cmp_eq_u32_e32 vcc, 0, v2
	s_and_saveexec_b64 s[12:13], vcc
	s_cbranch_execz .LBB0_491
	s_bcnt1_i32_b64 s3, s[10:11]
	v_mov_b32_e32 v3, 0xc83000
	v_mov_b32_e32 v4, s3
	global_atomic_add v3, v3, v4, s[70:71] offset:1024 sc0

; __device__ __forceinline__ unsigned xb_add(unsigned* p, unsigned v) { return __hip_atomic_fetch_add(p, v, __ATOMIC_RELAXED, __HIP_MEMORY_SCOPE_AGENT); }
; __device__ __forceinline__ void xcd_barrier(const XcdBarrier& b) {
;     ...
;             __builtin_amdgcn_fence(__ATOMIC_ACQUIRE, "agent");
;             xb_add(&bar[XB_XGEN(b.x)], 1u);
.LBB0_505:
	s_or_b64 exec, exec, s[10:11]
	s_mov_b64 s[10:11], exec
	v_mbcnt_lo_u32_b32 v1, s10, 0
	v_mbcnt_hi_u32_b32 v1, s11, v1
	v_cmp_eq_u32_e32 vcc, 0, v1
	s_waitcnt vmcnt(0)
	s_bitcmp1_b32 s100, 1
	s_cbranch_scc1 .Llb_0
	buffer_inv sc1
.Llb_0:
	s_and_saveexec_b64 s[12:13], vcc
	s_cbranch_execz .LBB0_507
	s_bcnt1_i32_b64 s3, s[10:11]
	v_mov_b32_e32 v1, 0x2000
	v_mov_b32_e32 v2, s3
	global_atomic_add v1, v2, s[4:5] offset:1024

; __device__ void final_phase(const Params& p) {
;     const int tid = threadIdx.x, w = tid >> 6, lane = tid & 63;
;     const float* modp = (const float*)(p.ws + WS_MODP);
;     const bf16_t* Y = (const bf16_t*)(p.ws + WS_QF);
;     const int rows_per = NLAT / gridDim.x;
;     for (int r0 = blockIdx.x * rows_per; r0 < NLAT; r0 += gridDim.x * rows_per) {
;         const int rend = min(r0 + rows_per, NLAT);
;         int curb = -1; f32x4 gt[4], g[4];
; #pragma unroll
;         for (int c = 0; c < 4; ++c) { g[c] = *(const f32x4*)(p.final_norm_g + c * 256 + lane * 4); gt[c] = (f32x4){0.f, 0.f, 0.f, 0.f}; }
;         for (int row = r0 + w * 2; row < rend; row += 16) {
.LBB0_509:
	s_cmp_lt_i32 s72, 7
	s_cselect_b64 s[4:5], -1, 0
	s_and_b64 s[4:5], s[4:5], s[6:7]
	s_andn2_b64 vcc, exec, s[4:5]
	s_cbranch_vccnz .LBB0_518
	s_load_dword s0, s[0:1], 0x98
	s_waitcnt lgkmcnt(0)
	v_cvt_f32_u32_e32 v1, s0
	s_sub_i32 s1, 0, s0
	v_rcp_iflag_f32_e32 v1, v1
	s_nop 0
	v_mul_f32_e32 v1, 0x4f7ffffe, v1
	v_cvt_u32_f32_e32 v1, v1
	s_nop 0
	v_readfirstlane_b32 s3, v1
	s_mul_i32 s1, s1, s3
	s_mul_hi_u32 s1, s3, s1
	s_add_i32 s3, s3, s1
	s_lshr_b32 s1, s3, 17
	s_mul_i32 s3, s1, s0
	s_sub_i32 s3, 0x8000, s3
	s_add_i32 s4, s1, 1
	s_sub_i32 s5, s3, s0
	s_cmp_ge_u32 s3, s0
	s_cselect_b32 s1, s4, s1
	s_cselect_b32 s3, s5, s3
	s_add_i32 s4, s1, 1
	s_cmp_ge_u32 s3, s0
	s_cselect_b32 s3, s4, s1
	s_and_b32 s4, s2, 7
	s_lshl_b32 s4, s4, 5
	s_lshr_b32 s5, s2, 3
	s_add_i32 s4, s4, s5
	s_bitcmp1_b32 s100, 0
	s_cselect_b32 s4, s4, s2
	s_mul_i32 s12, s3, s4
	s_cmpk_gt_i32 s12, 0x7fff
	s_cbranch_scc1 .LBB0_518
	v_lshlrev_b32_e32 v1, 2, v0
	s_waitcnt vmcnt(0)
	v_and_b32_e32 v2, 0xfc, v1
	v_mov_b32_e32 v33, 0
	v_lshlrev_b32_e32 v32, 2, v2
	v_and_b32_e32 v3, 63, v0
	v_lshrrev_b32_e32 v1, 5, v0
	s_mul_i32 s13, s3, s0
	v_lshl_add_u64 v[34:35], s[66:67], 0, v[32:33]
	v_lshl_add_u64 v[4:5], s[48:49], 0, v[32:33]
	s_mov_b64 s[0:1], 0x2000
	v_lshlrev_b32_e32 v32, 3, v3
	v_and_b32_e32 v45, 14, v1
	v_lshl_add_u64 v[36:37], v[4:5], 0, s[0:1]
	v_lshl_add_u64 v[0:1], s[70:71], 0, v[32:33]
	s_mov_b64 s[0:1], 0x5100000
	v_lshl_add_u64 v[38:39], v[0:1], 0, s[0:1]
	v_mbcnt_lo_u32_b32 v0, -1, 0
	v_mbcnt_hi_u32_b32 v52, -1, v0
	v_and_b32_e32 v0, 64, v52
	v_add_u32_e32 v40, s12, v45
	v_lshlrev_b32_e32 v42, 4, v3
	v_mov_b32_e32 v43, v33
	v_lshlrev_b32_e32 v32, 2, v2
	s_movk_i32 s14, 0x1000
	s_mov_b32 s2, 0x3a800000
	s_mov_b32 s15, 0x800000
	s_mov_b64 s[4:5], 0x8000
	s_mov_b64 s[6:7], 0x10000
	v_add_u32_e32 v53, 64, v0
	v_xor_b32_e32 v54, 32, v52
	v_xor_b32_e32 v55, 16, v52
	v_xor_b32_e32 v56, 8, v52
	v_xor_b32_e32 v57, 4, v52
	v_xor_b32_e32 v58, 2, v52
	v_xor_b32_e32 v59, 1, v52
	v_mov_b32_e32 v44, 0x358637bd
	s_branch .LBB0_513

; #define LAS __attribute__((address_space(3)))
; __global__ void __launch_bounds__(NTHR, 2) hymba_fwd(Params p) {
;     extern __shared__ __attribute__((aligned(16))) unsigned char lds_raw[];
;     LAS unsigned char* lds = (LAS unsigned char*)lds_raw;
	.amdhsa_kernel _Z9hymba_fwd6Params
		.amdhsa_group_segment_fixed_size 25600
		.amdhsa_private_segment_fixed_size 0
		.amdhsa_kernarg_size 408
		.amdhsa_user_sgpr_count 2
		.amdhsa_user_sgpr_dispatch_ptr 0
		.amdhsa_user_sgpr_queue_ptr 0
		.amdhsa_user_sgpr_kernarg_segment_ptr 1
		.amdhsa_user_sgpr_dispatch_id 0
		.amdhsa_user_sgpr_kernarg_preload_length 0
		.amdhsa_user_sgpr_kernarg_preload_offset 0
		.amdhsa_user_sgpr_private_segment_size 0
		.amdhsa_uses_dynamic_stack 0
		.amdhsa_enable_private_segment 0
		.amdhsa_system_sgpr_workgroup_id_x 1
		.amdhsa_system_sgpr_workgroup_id_y 0
		.amdhsa_system_sgpr_workgroup_id_z 0
		.amdhsa_system_sgpr_workgroup_info 0
		.amdhsa_system_vgpr_workitem_id 0
		.amdhsa_next_free_vgpr 256
		.amdhsa_next_free_sgpr 102
		.amdhsa_accum_offset 256
		.amdhsa_reserve_vcc 1
		.amdhsa_float_round_mode_32 0
		.amdhsa_float_round_mode_16_64 0
		.amdhsa_float_denorm_mode_32 3
		.amdhsa_float_denorm_mode_16_64 3
		.amdhsa_dx10_clamp 1
		.amdhsa_ieee_mode 1
		.amdhsa_fp16_overflow 0
		.amdhsa_tg_split 0
		.amdhsa_exception_fp_ieee_invalid_op 0
		.amdhsa_exception_fp_denorm_src 0
		.amdhsa_exception_fp_ieee_div_zero 0
		.amdhsa_exception_fp_ieee_overflow 0
		.amdhsa_exception_fp_ieee_underflow 0
		.amdhsa_exception_fp_ieee_inexact 0
		.amdhsa_exception_int_div_zero 0
	.end_amdhsa_kernel

; #define LAS __attribute__((address_space(3)))
; __global__ void __launch_bounds__(NTHR, 2) hymba_fwd(Params p) {
;     extern __shared__ __attribute__((aligned(16))) unsigned char lds_raw[];
;     LAS unsigned char* lds = (LAS unsigned char*)lds_raw;
amdhsa.kernels:
  - .agpr_count:     0
    .args:
      - .offset:         0
        .size:           152
        .value_kind:     by_value
      - .offset:         152
        .size:           4
        .value_kind:     hidden_block_count_x
      - .offset:         156
        .size:           4
        .value_kind:     hidden_block_count_y
      - .offset:         160
        .size:           4
        .value_kind:     hidden_block_count_z
      - .offset:         164
        .size:           2
        .value_kind:     hidden_group_size_x
      - .offset:         166
        .size:           2
        .value_kind:     hidden_group_size_y
      - .offset:         168
        .size:           2
        .value_kind:     hidden_group_size_z
      - .offset:         170
        .size:           2
        .value_kind:     hidden_remainder_x
      - .offset:         172
        .size:           2
        .value_kind:     hidden_remainder_y
      - .offset:         174
        .size:           2
        .value_kind:     hidden_remainder_z
      - .offset:         192
        .size:           8
        .value_kind:     hidden_global_offset_x
      - .offset:         200
        .size:           8
        .value_kind:     hidden_global_offset_y
      - .offset:         208
        .size:           8
        .value_kind:     hidden_global_offset_z
      - .offset:         216
        .size:           2
        .value_kind:     hidden_grid_dims
      - .offset:         272
        .size:           4
        .value_kind:     hidden_dynamic_lds_size
    .group_segment_fixed_size: 25600
    .kernarg_segment_align: 8
    .kernarg_segment_size: 408
    .language:       OpenCL C
    .language_version:
      - 2
      - 0
    .max_flat_workgroup_size: 512
    .name:           _Z9hymba_fwd6Params
    .private_segment_fixed_size: 0
    .sgpr_count:     108
    .sgpr_spill_count: 4
    .symbol:         _Z9hymba_fwd6Params.kd
    .uniform_work_group_size: 1
    .uses_dynamic_stack: false
    .vgpr_count:     256
    .vgpr_spill_count: 0
    .wavefront_size: 64
